# MLA row sum kept in eight running partial sums next to the exps (per-tile add tree removed)
# speedup vs baseline: 1.0275x; 1.0035x over previous
; DI u32x2 pk4(float a, float b, float c, float d) { u32x2 r; r.x = pk2(a, b); r.y = pk2(c, d); return r; }
;     ...
;     { const auto sw = __builtin_amdgcn_permlane32_swap(__float_as_uint(lsum), __float_as_uint(lsum), false, false);
;       lsum = __uint_as_float(sw[0]) + __uint_as_float(sw[1]); }
;     const float inv = 1.0f / lsum;
;     {
;         unsigned char* sb = lds + 2 * STG + wid * (32 * 144);
; #pragma unroll
;         for (int d = 0; d < 2; ++d)
; #pragma unroll
;             for (int g = 0; g < 4; ++g)
;                 *(u32x2*)(sb + ln * 144 + (d * 32 + 8 * g + 4 * h) * 2) = pk4(o[d][4 * g] * inv, o[d][4 * g + 1] * inv, o[d][4 * g + 2] * inv, o[d][4 * g + 3] * inv);
;         __builtin_amdgcn_fence(__ATOMIC_RELEASE, "wavefront");
;         __builtin_amdgcn_wave_barrier();
;         __builtin_amdgcn_fence(__ATOMIC_ACQUIRE, "wavefront");
; #pragma unroll
;         for (int ps = 0; ps < 4; ++ps) {
;             const int row = ps * 8 + (lane >> 3), ch = lane & 7;
;             const u32x4 v = *(const u32x4*)(sb + row * 144 + ch * 16);
;             *(u32x4*)(obase + (size_t)(qw0 + row) * ldo + ch * 8) = v;
;         }
.LBB0_736:
	v_add_f32_e32 v248, v248, v249
	v_add_f32_e32 v250, v250, v251
	v_add_f32_e32 v252, v252, v253
	v_add_f32_e32 v254, v254, v255
	v_add_f32_e32 v248, v248, v250
	v_add_f32_e32 v252, v252, v254
	v_add_f32_e32 v220, v248, v252
	v_mov_b32_e32 v1, v220
	s_nop 1
	v_permlane32_swap_b32_e32 v220, v1
	v_add_f32_e32 v1, v220, v1
	v_div_scale_f32 v34, s[8:9], v1, v1, 1.0
	v_rcp_f32_e32 v35, v34
	s_mov_b64 s[8:9], 0
	v_fma_f32 v36, -v34, v35, 1.0
	v_fmac_f32_e32 v35, v36, v35
	v_div_scale_f32 v36, vcc, 1.0, v1, 1.0
	v_mul_f32_e32 v37, v36, v35
	v_fma_f32 v38, -v34, v37, v36
	v_fmac_f32_e32 v37, v38, v35
	v_fma_f32 v34, -v34, v37, v36
	v_div_fmas_f32 v34, v34, v35, v37
	v_div_fixup_f32 v34, v34, v1, 1.0
	v_pk_mul_f32 v[18:19], v[18:19], v[34:35] op_sel_hi:[1,0]
	v_pk_mul_f32 v[20:21], v[20:21], v[34:35] op_sel_hi:[1,0]
	v_pk_mul_f32 v[2:3], v[2:3], v[34:35] op_sel_hi:[1,0]
	v_pk_mul_f32 v[4:5], v[4:5], v[34:35] op_sel_hi:[1,0]
	v_cvt_pk_bf16_f32 v18, v18, v19
	v_cvt_pk_bf16_f32 v19, v20, v21
	v_pk_mul_f32 v[20:21], v[22:23], v[34:35] op_sel_hi:[1,0]
	v_pk_mul_f32 v[22:23], v[24:25], v[34:35] op_sel_hi:[1,0]
	v_cvt_pk_bf16_f32 v2, v2, v3
	v_cvt_pk_bf16_f32 v3, v4, v5
	v_pk_mul_f32 v[4:5], v[6:7], v[34:35] op_sel_hi:[1,0]
	v_pk_mul_f32 v[6:7], v[8:9], v[34:35] op_sel_hi:[1,0]
	v_cvt_pk_bf16_f32 v20, v20, v21
	v_cvt_pk_bf16_f32 v21, v22, v23
	v_add_u32_e32 v1, 0xb000, v214
	v_cvt_pk_bf16_f32 v4, v4, v5
	v_cvt_pk_bf16_f32 v5, v6, v7
	ds_write2_b64 v1, v[18:19], v[20:21] offset0:192 offset1:194
	v_pk_mul_f32 v[18:19], v[26:27], v[34:35] op_sel_hi:[1,0]
	v_pk_mul_f32 v[20:21], v[28:29], v[34:35] op_sel_hi:[1,0]
	ds_write2_b64 v1, v[2:3], v[4:5] offset0:200 offset1:202
	v_pk_mul_f32 v[2:3], v[10:11], v[34:35] op_sel_hi:[1,0]
	v_pk_mul_f32 v[4:5], v[12:13], v[34:35] op_sel_hi:[1,0]
	v_cvt_pk_bf16_f32 v18, v18, v19
	v_cvt_pk_bf16_f32 v19, v20, v21
	v_pk_mul_f32 v[20:21], v[30:31], v[34:35] op_sel_hi:[1,0]
	v_pk_mul_f32 v[22:23], v[32:33], v[34:35] op_sel_hi:[1,0]
	v_cvt_pk_bf16_f32 v2, v2, v3
	v_cvt_pk_bf16_f32 v3, v4, v5
	v_pk_mul_f32 v[4:5], v[14:15], v[34:35] op_sel_hi:[1,0]
	v_pk_mul_f32 v[6:7], v[16:17], v[34:35] op_sel_hi:[1,0]
	v_cvt_pk_bf16_f32 v20, v20, v21
	v_cvt_pk_bf16_f32 v21, v22, v23
	v_cvt_pk_bf16_f32 v4, v4, v5
	v_cvt_pk_bf16_f32 v5, v6, v7
	ds_write2_b64 v1, v[18:19], v[20:21] offset0:196 offset1:198
	ds_write2_b64 v1, v[2:3], v[4:5] offset0:204 offset1:206
	ds_read_b128 v[2:5], v215 offset:46592
	v_or_b32_e32 v6, v159, v202
	v_ashrrev_i32_e32 v7, 31, v6
	v_lshlrev_b64 v[6:7], 11, v[6:7]
	v_lshl_add_u64 v[10:11], v[168:169], 0, v[6:7]
	ds_read_b128 v[6:9], v215 offset:47744
	s_waitcnt lgkmcnt(1)
	global_store_dwordx4 v[10:11], v[2:5], off
	s_and_b64 vcc, exec, s[48:49]
	s_nop 0
	v_or_b32_e32 v2, v159, v188
	v_ashrrev_i32_e32 v3, 31, v2
	v_lshlrev_b64 v[2:3], 11, v[2:3]
	v_lshl_add_u64 v[2:3], v[168:169], 0, v[2:3]
	s_waitcnt lgkmcnt(0)
	global_store_dwordx4 v[2:3], v[6:9], off
	ds_read_b128 v[2:5], v215 offset:48896
	s_nop 0
	v_add_u32_e32 v6, v159, v192
	v_ashrrev_i32_e32 v7, 31, v6
	v_lshlrev_b64 v[6:7], 11, v[6:7]
	v_lshl_add_u64 v[10:11], v[168:169], 0, v[6:7]
	ds_read_b128 v[6:9], v215 offset:50048
	s_waitcnt lgkmcnt(1)
	global_store_dwordx4 v[10:11], v[2:5], off
	s_nop 1
	v_add_u32_e32 v2, v159, v194
	v_ashrrev_i32_e32 v3, 31, v2
	v_lshlrev_b64 v[2:3], 11, v[2:3]
	v_lshl_add_u64 v[2:3], v[168:169], 0, v[2:3]
	s_waitcnt lgkmcnt(0)
	global_store_dwordx4 v[2:3], v[6:9], off
	s_cbranch_vccnz .LBB0_734

;     ...
;     f32x16 o[2];
; #pragma unroll
;     for (int d = 0; d < 2; ++d)
; #pragma unroll
;         for (int r = 0; r < 16; ++r) o[d][r] = 0.f;
;     float m = -INFINITY, lsum = 0.f;
;     ...
;     const int jlast = nkt - 1;
;     gload(jlast); lstore(0);
;     __syncthreads();
;     m = -1e30f;
.LBB0_745:
	s_or_b64 exec, exec, s[10:11]
	s_and_b32 s10, s13, 0x1fc0
	v_add_u32_e32 v1, s12, v151
	v_subrev_u32_e32 v219, s10, v1
	v_add_u32_e32 v1, s10, v184
	s_xor_b64 s[48:49], s[8:9], -1
	v_mad_i64_i32 v[176:177], s[8:9], v1, s70, v[172:173]
	v_add_u32_e32 v1, s10, v189
	v_mov_b32_e32 v14, v0
	v_mov_b32_e32 v15, v0
	v_mad_i64_i32 v[178:179], s[8:9], v1, s70, v[174:175]
	v_mov_b32_e32 v1, v0
	v_mov_b32_e32 v2, v0
	v_mov_b32_e32 v3, v0
	v_mov_b32_e32 v4, v0
	v_mov_b32_e32 v5, v0
	v_mov_b32_e32 v6, v0
	v_mov_b32_e32 v7, v0
	v_mov_b32_e32 v8, v0
	v_mov_b32_e32 v9, v0
	v_mov_b32_e32 v10, v0
	v_mov_b32_e32 v11, v0
	v_mov_b32_e32 v12, v0
	v_mov_b32_e32 v13, v0
	v_mov_b64_e32 v[32:33], v[14:15]
	v_mov_b64_e32 v[30:31], v[12:13]
	v_mov_b64_e32 v[28:29], v[10:11]
	v_mov_b64_e32 v[26:27], v[8:9]
	v_mov_b64_e32 v[24:25], v[6:7]
	v_mov_b64_e32 v[22:23], v[4:5]
	v_mov_b64_e32 v[20:21], v[2:3]
	v_mov_b64_e32 v[18:19], v[0:1]
	v_mov_b64_e32 v[16:17], v[14:15]
	s_lshr_b32 s2, s13, 6
	v_add_u32_e32 v218, 31, v159
	s_sub_i32 s42, s10, 64
	s_mov_b32 s60, 0
	v_mov_b32_e32 v220, 0
	v_mov_b32_e32 v248, 0
	v_mov_b32_e32 v249, 0
	v_mov_b32_e32 v250, 0
	v_mov_b32_e32 v251, 0
	v_mov_b32_e32 v252, 0
	v_mov_b32_e32 v253, 0
	v_mov_b32_e32 v254, 0
	v_mov_b32_e32 v255, 0
	v_mov_b32_e32 v221, 0xf149f2ca
	v_mov_b32_e32 v230, 0
	v_mov_b32_e32 v231, 0
	v_mov_b32_e32 v232, 0
	v_mov_b32_e32 v233, 0
	v_mov_b32_e32 v234, 0
	v_mov_b32_e32 v235, 0
	v_mov_b32_e32 v236, 0
	v_mov_b32_e32 v237, 0
	v_mov_b32_e32 v238, 0
	v_mov_b32_e32 v239, 0
	v_mov_b32_e32 v240, 0
	v_mov_b32_e32 v241, 0
	v_mov_b32_e32 v242, 0
	v_mov_b32_e32 v243, 0
	v_mov_b32_e32 v244, 0
	v_mov_b32_e32 v245, 0
	v_mov_b32_e32 v246, 0
	v_mov_b64_e32 v[14:15], v[12:13]
	v_mov_b64_e32 v[12:13], v[10:11]
	v_mov_b64_e32 v[10:11], v[8:9]
	v_mov_b64_e32 v[8:9], v[6:7]
	v_mov_b64_e32 v[6:7], v[4:5]
	v_mov_b64_e32 v[4:5], v[2:3]
	v_mov_b64_e32 v[2:3], v[0:1]
	s_waitcnt vmcnt(0)
	ds_write2_b64 v213, v[98:99], v[100:101] offset1:1
	s_waitcnt lgkmcnt(0)
	s_barrier
	s_branch .LBB0_748

;     ...
;             float mx = fmaxf(mxa[0], mxa[1]);
;             { const auto sw = __builtin_amdgcn_permlane32_swap(__float_as_uint(mx), __float_as_uint(mx), false, false);
;               mx = fmaxf(__uint_as_float(sw[0]), __uint_as_float(sw[1])); }
;             if (__builtin_amdgcn_ballot_w64(mx > m + 8.0f) != 0ull) {
;                 const float mn = fmaxf(m, mx);
;                 const float alpha = __builtin_amdgcn_exp2f(m - mn);
;                 m = mn;
;                 lsum *= alpha;
; #pragma unroll
;                 for (int d = 0; d < 2; ++d)
; #pragma unroll
;                     for (int r = 0; r < 16; ++r) o[d][r] *= alpha;
;             }
;             float ps0 = 0.f, ps1 = 0.f, ps2 = 0.f, ps3 = 0.f;
; #pragma unroll
;             for (int t2 = 0; t2 < 2; ++t2)
; #pragma unroll
;                 for (int r = 0; r < 16; r += 4) {
;                     const float e0 = __builtin_amdgcn_exp2f(s[t2][r] - m), e1 = __builtin_amdgcn_exp2f(s[t2][r + 1] - m);
;                     const float e2 = __builtin_amdgcn_exp2f(s[t2][r + 2] - m), e3 = __builtin_amdgcn_exp2f(s[t2][r + 3] - m);
;                     s[t2][r] = e0; s[t2][r + 1] = e1; s[t2][r + 2] = e2; s[t2][r + 3] = e3;
;                     ps0 += e0; ps1 += e1; ps2 += e2; ps3 += e3;
;                 }
;             lsum += (ps0 + ps1) + (ps2 + ps3);
.LBB0_757:
	s_or_b64 exec, exec, s[68:69]
	v_max3_f32 v1, v50, v51, v52
	v_max3_f32 v222, v53, v54, v55
	v_max3_f32 v223, v56, v57, v58
	v_max3_f32 v224, v59, v60, v61
	v_max3_f32 v225, v62, v63, v64
	v_max3_f32 v1, v1, v222, v223
	v_max3_f32 v222, v224, v225, v65
	v_max_f32_e32 v223, v35, v35
	v_max_f32_e32 v224, v34, v34
	v_max_f32_e32 v223, v224, v223
	v_max3_f32 v224, v37, v38, v39
	v_max3_f32 v226, v43, v44, v45
	v_max3_f32 v227, v46, v47, v48
	v_max3_f32 v225, v40, v41, v42
	v_max3_f32 v223, v223, v36, v224
	v_max3_f32 v224, v226, v227, v49
	v_max3_f32 v223, v223, v225, v224
	v_max3_f32 v1, v1, v222, v223
	v_mov_b32_e32 v222, v1
	s_nop 1
	v_permlane32_swap_b32_e32 v1, v222
	v_max_f32_e32 v222, v222, v222
	v_max_f32_e32 v1, v1, v1
	v_max_f32_e32 v1, v1, v222
	v_add_f32_e32 v1, v1, v246
	v_add_f32_e32 v222, 0x41000000, v221
	v_cmp_gt_f32_e32 vcc, v1, v222
	s_cbranch_vccz .LBB0_759
	v_max_f32_e32 v1, v1, v1
	v_max_f32_e32 v222, v221, v221
	v_max_f32_e32 v1, v222, v1
	v_sub_f32_e32 v221, v221, v1
	v_exp_f32_e32 v222, v221
	v_mov_b32_e32 v221, v1
	v_cmp_lt_f32_e32 vcc, 0xefa18f08, v1
	s_nop 1
	v_cndmask_b32_e32 v224, 0, v1, vcc
	v_sub_f32_e32 v223, v224, v246
	v_sub_f32_e32 v50, v50, v223
	v_sub_f32_e32 v51, v51, v223
	v_sub_f32_e32 v52, v52, v223
	v_sub_f32_e32 v53, v53, v223
	v_sub_f32_e32 v54, v54, v223
	v_sub_f32_e32 v55, v55, v223
	v_sub_f32_e32 v56, v56, v223
	v_sub_f32_e32 v57, v57, v223
	v_sub_f32_e32 v58, v58, v223
	v_sub_f32_e32 v59, v59, v223
	v_sub_f32_e32 v60, v60, v223
	v_sub_f32_e32 v61, v61, v223
	v_sub_f32_e32 v62, v62, v223
	v_sub_f32_e32 v63, v63, v223
	v_sub_f32_e32 v64, v64, v223
	v_sub_f32_e32 v65, v65, v223
	v_sub_f32_e32 v34, v34, v223
	v_sub_f32_e32 v35, v35, v223
	v_sub_f32_e32 v36, v36, v223
	v_sub_f32_e32 v37, v37, v223
	v_sub_f32_e32 v38, v38, v223
	v_sub_f32_e32 v39, v39, v223
	v_sub_f32_e32 v40, v40, v223
	v_sub_f32_e32 v41, v41, v223
	v_sub_f32_e32 v42, v42, v223
	v_sub_f32_e32 v43, v43, v223
	v_sub_f32_e32 v44, v44, v223
	v_sub_f32_e32 v45, v45, v223
	v_sub_f32_e32 v46, v46, v223
	v_sub_f32_e32 v47, v47, v223
	v_sub_f32_e32 v48, v48, v223
	v_sub_f32_e32 v49, v49, v223
	v_mov_b32_e32 v246, v224
	v_sub_f32_e32 v230, 0, v224
	v_sub_f32_e32 v231, 0, v224
	v_sub_f32_e32 v232, 0, v224
	v_sub_f32_e32 v233, 0, v224
	v_sub_f32_e32 v234, 0, v224
	v_sub_f32_e32 v235, 0, v224
	v_sub_f32_e32 v236, 0, v224
	v_sub_f32_e32 v237, 0, v224
	v_sub_f32_e32 v238, 0, v224
	v_sub_f32_e32 v239, 0, v224
	v_sub_f32_e32 v240, 0, v224
	v_sub_f32_e32 v241, 0, v224
	v_sub_f32_e32 v242, 0, v224
	v_sub_f32_e32 v243, 0, v224
	v_sub_f32_e32 v244, 0, v224
	v_sub_f32_e32 v245, 0, v224
	v_pk_mul_f32 v[32:33], v[32:33], v[222:223] op_sel_hi:[1,0]
	v_pk_mul_f32 v[30:31], v[30:31], v[222:223] op_sel_hi:[1,0]
	v_pk_mul_f32 v[28:29], v[28:29], v[222:223] op_sel_hi:[1,0]
	v_pk_mul_f32 v[26:27], v[26:27], v[222:223] op_sel_hi:[1,0]
	v_pk_mul_f32 v[24:25], v[24:25], v[222:223] op_sel_hi:[1,0]
	v_pk_mul_f32 v[22:23], v[22:23], v[222:223] op_sel_hi:[1,0]
	v_pk_mul_f32 v[20:21], v[20:21], v[222:223] op_sel_hi:[1,0]
	v_pk_mul_f32 v[18:19], v[18:19], v[222:223] op_sel_hi:[1,0]
	v_pk_mul_f32 v[16:17], v[16:17], v[222:223] op_sel_hi:[1,0]
	v_pk_mul_f32 v[14:15], v[14:15], v[222:223] op_sel_hi:[1,0]
	v_pk_mul_f32 v[12:13], v[12:13], v[222:223] op_sel_hi:[1,0]
	v_pk_mul_f32 v[10:11], v[10:11], v[222:223] op_sel_hi:[1,0]
	v_pk_mul_f32 v[8:9], v[8:9], v[222:223] op_sel_hi:[1,0]
	v_pk_mul_f32 v[6:7], v[6:7], v[222:223] op_sel_hi:[1,0]
	v_pk_mul_f32 v[4:5], v[4:5], v[222:223] op_sel_hi:[1,0]
	v_pk_mul_f32 v[2:3], v[2:3], v[222:223] op_sel_hi:[1,0]
	v_mul_f32_e32 v248, v248, v222
	v_mul_f32_e32 v249, v249, v222
	v_mul_f32_e32 v250, v250, v222
	v_mul_f32_e32 v251, v251, v222
	v_mul_f32_e32 v252, v252, v222
	v_mul_f32_e32 v253, v253, v222
	v_mul_f32_e32 v254, v254, v222
	v_mul_f32_e32 v255, v255, v222
.LBB0_759:
	v_exp_f32_e32 v50, v50
	v_exp_f32_e32 v222, v51
	v_add_f32_e32 v248, v248, v50
	v_exp_f32_e32 v51, v52
	v_add_f32_e32 v249, v249, v222
	v_exp_f32_e32 v223, v53
	v_add_f32_e32 v250, v250, v51
	v_exp_f32_e32 v52, v54
	v_add_f32_e32 v251, v251, v223
	v_exp_f32_e32 v54, v55
	v_add_f32_e32 v252, v252, v52
	v_exp_f32_e32 v53, v56
	v_add_f32_e32 v253, v253, v54
	v_exp_f32_e32 v55, v57
	v_add_f32_e32 v254, v254, v53
	v_exp_f32_e32 v56, v58
	v_add_f32_e32 v255, v255, v55
	v_exp_f32_e32 v58, v59
	v_add_f32_e32 v248, v248, v56
	v_exp_f32_e32 v57, v60
	v_add_f32_e32 v249, v249, v58
	v_exp_f32_e32 v59, v61
	v_add_f32_e32 v250, v250, v57
	v_exp_f32_e32 v60, v62
	v_add_f32_e32 v251, v251, v59
	v_exp_f32_e32 v62, v63
	v_add_f32_e32 v252, v252, v60
	v_exp_f32_e32 v61, v64
	v_add_f32_e32 v253, v253, v62
	v_exp_f32_e32 v63, v65
	v_add_f32_e32 v254, v254, v61
	v_exp_f32_e32 v64, v34
	v_add_f32_e32 v255, v255, v63
	v_exp_f32_e32 v224, v35
	v_add_f32_e32 v248, v248, v64
	v_exp_f32_e32 v65, v36
	v_add_f32_e32 v249, v249, v224
	v_exp_f32_e32 v225, v37
	v_add_f32_e32 v250, v250, v65
	v_cvt_pk_bf16_f32 v34, v50, v222
	v_add_f32_e32 v251, v251, v225
	v_cvt_pk_bf16_f32 v35, v51, v223
	v_cvt_pk_bf16_f32 v36, v52, v54
	v_cvt_pk_bf16_f32 v37, v53, v55
	s_waitcnt lgkmcnt(7)
	s_nop 0
	v_mfma_f32_32x32x16_bf16 v[18:33], v[130:133], v[34:37], v[18:33]
	v_exp_f32_e32 v38, v38
	v_exp_f32_e32 v226, v39
	v_add_f32_e32 v252, v252, v38
	v_exp_f32_e32 v39, v40
	v_add_f32_e32 v253, v253, v226
	v_exp_f32_e32 v227, v41
	v_add_f32_e32 v254, v254, v39
	s_waitcnt lgkmcnt(5)
	v_add_f32_e32 v255, v255, v227
	v_mfma_f32_32x32x16_bf16 v[2:17], v[126:129], v[34:37], v[2:17]
	v_cvt_pk_bf16_f32 v34, v56, v58
	v_cvt_pk_bf16_f32 v35, v57, v59
	v_cvt_pk_bf16_f32 v36, v60, v62
	v_cvt_pk_bf16_f32 v37, v61, v63
	v_exp_f32_e32 v40, v42
	s_nop 0
	v_mfma_f32_32x32x16_bf16 v[18:33], v[122:125], v[34:37], v[18:33]
	v_add_f32_e32 v248, v248, v40
	v_exp_f32_e32 v42, v43
	v_exp_f32_e32 v41, v44
	v_add_f32_e32 v249, v249, v42
	v_exp_f32_e32 v43, v45
	v_add_f32_e32 v250, v250, v41
	v_exp_f32_e32 v44, v46
	v_add_f32_e32 v251, v251, v43
	s_waitcnt lgkmcnt(4)
	v_add_f32_e32 v252, v252, v44
	v_mfma_f32_32x32x16_bf16 v[2:17], v[118:121], v[34:37], v[2:17]
	v_cvt_pk_bf16_f32 v34, v64, v224
	v_cvt_pk_bf16_f32 v35, v65, v225
	v_cvt_pk_bf16_f32 v36, v38, v226
	v_cvt_pk_bf16_f32 v37, v39, v227
	v_exp_f32_e32 v46, v47
	s_waitcnt lgkmcnt(3)
	v_add_f32_e32 v253, v253, v46
	v_mfma_f32_32x32x16_bf16 v[18:33], v[114:117], v[34:37], v[18:33]
	v_exp_f32_e32 v45, v48
	v_exp_f32_e32 v47, v49
	v_add_f32_e32 v254, v254, v45
	s_waitcnt lgkmcnt(2)
	v_add_f32_e32 v255, v255, v47
	v_mfma_f32_32x32x16_bf16 v[2:17], v[110:113], v[34:37], v[2:17]
	v_cvt_pk_bf16_f32 v34, v40, v42
	v_cvt_pk_bf16_f32 v35, v41, v43
	v_cvt_pk_bf16_f32 v36, v44, v46
	v_cvt_pk_bf16_f32 v37, v45, v47
	s_waitcnt lgkmcnt(1)
	s_nop 0
	v_mfma_f32_32x32x16_bf16 v[18:33], v[106:109], v[34:37], v[18:33]
	s_nop 0
	s_waitcnt lgkmcnt(0)
	v_mfma_f32_32x32x16_bf16 v[2:17], v[102:105], v[34:37], v[2:17]
